# residual epilogues: first base rows requested at the tile start into registers the K loop does not use
# baseline (speedup 1.0000x reference)
.LBB0_728:
	s_ashr_i32 s45, s44, 31
	s_lshl_b64 s[50:51], s[44:45], 19
	s_add_u32 s50, s11, s50
	s_addc_u32 s51, s17, s51
	s_and_b64 s[54:55], s[2:3], exec
	s_cselect_b32 s45, s51, s59
	s_cselect_b32 s78, s50, s58
	s_ashr_i32 s35, s34, 31
	s_lshl_b64 s[54:55], s[34:35], 19
	s_add_u32 s54, s64, s54
	s_addc_u32 s55, s65, s55
	s_and_b64 s[62:63], s[2:3], exec
	s_cselect_b32 s35, s55, s61
	s_cselect_b32 s79, s54, s60
	s_add_u32 s58, s58, 0x40080
	s_addc_u32 s59, s59, 0
	s_add_u32 s80, s60, 0x100
	s_addc_u32 s81, s61, 0
	s_mov_b32 s82, -2
	v_mov_b64_e32 v[0:1], 0
	v_mov_b64_e32 v[2:3], 0
	v_mov_b64_e32 v[4:5], 0
	v_mov_b64_e32 v[6:7], 0
	v_mov_b64_e32 v[8:9], 0
	v_mov_b64_e32 v[10:11], 0
	v_mov_b64_e32 v[12:13], 0
	v_mov_b64_e32 v[14:15], 0
	v_mov_b64_e32 v[16:17], 0
	v_mov_b64_e32 v[18:19], 0
	v_mov_b64_e32 v[20:21], 0
	v_mov_b64_e32 v[22:23], 0
	v_mov_b64_e32 v[24:25], 0
	v_mov_b64_e32 v[26:27], 0
	v_mov_b64_e32 v[28:29], 0
	v_mov_b64_e32 v[30:31], 0
	v_mov_b64_e32 v[32:33], 0
	v_mov_b64_e32 v[34:35], 0
	v_mov_b64_e32 v[36:37], 0
	v_mov_b64_e32 v[38:39], 0
	v_mov_b64_e32 v[40:41], 0
	v_mov_b64_e32 v[42:43], 0
	v_mov_b64_e32 v[44:45], 0
	v_mov_b64_e32 v[46:47], 0
	v_mov_b64_e32 v[48:49], 0
	v_mov_b64_e32 v[50:51], 0
	v_mov_b64_e32 v[52:53], 0
	v_mov_b64_e32 v[54:55], 0
	v_mov_b64_e32 v[56:57], 0
	v_mov_b64_e32 v[58:59], 0
	v_mov_b64_e32 v[60:61], 0
	v_mov_b64_e32 v[62:63], 0
	v_mov_b64_e32 v[64:65], 0
	v_mov_b64_e32 v[66:67], 0
	v_mov_b64_e32 v[68:69], 0
	v_mov_b64_e32 v[70:71], 0
	v_mov_b64_e32 v[72:73], 0
	v_mov_b64_e32 v[74:75], 0
	v_mov_b64_e32 v[76:77], 0
	v_mov_b64_e32 v[78:79], 0
	v_mov_b64_e32 v[80:81], 0
	v_mov_b64_e32 v[82:83], 0
	v_mov_b64_e32 v[84:85], 0
	v_mov_b64_e32 v[86:87], 0
	v_mov_b64_e32 v[88:89], 0
	v_mov_b64_e32 v[90:91], 0
	v_mov_b64_e32 v[92:93], 0
	v_mov_b64_e32 v[94:95], 0
	v_mov_b64_e32 v[96:97], 0
	v_mov_b64_e32 v[98:99], 0
	v_mov_b64_e32 v[100:101], 0
	v_mov_b64_e32 v[102:103], 0
	v_mov_b64_e32 v[104:105], 0
	v_mov_b64_e32 v[106:107], 0
	v_mov_b64_e32 v[108:109], 0
	v_mov_b64_e32 v[110:111], 0
	v_mov_b64_e32 v[112:113], 0
	v_mov_b64_e32 v[114:115], 0
	v_mov_b64_e32 v[116:117], 0
	v_mov_b64_e32 v[118:119], 0
	v_mov_b64_e32 v[120:121], 0
	v_mov_b64_e32 v[122:123], 0
	v_mov_b64_e32 v[124:125], 0
	v_mov_b64_e32 v[126:127], 0
	v_lshl_add_u32 v160, s1, 8, v142
	v_lshl_or_b32 v161, s0, 8, v144
	v_lshl_add_u32 v160, v160, 10, v161
	v_lshlrev_b32_e32 v160, 2, v160
	v_mov_b32_e32 v161, v160
	v_add_u32_e32 v162, 0x10000, v160
	global_load_dwordx4 v[222:225], v161, s[52:53]
	global_load_dwordx4 v[226:229], v161, s[52:53] offset:64
	global_load_dwordx4 v[230:233], v161, s[52:53] offset:512
	global_load_dwordx4 v[234:237], v161, s[52:53] offset:576
	global_load_dwordx4 v[238:241], v162, s[52:53]
	global_load_dwordx4 v[242:245], v162, s[52:53] offset:64
	global_load_dwordx4 v[246:249], v162, s[52:53] offset:512
	global_load_dwordx4 v[250:253], v162, s[52:53] offset:576

.LBB0_732:
	v_lshl_add_u32 v152, s1, 8, v142
	v_lshl_or_b32 v154, s0, 8, v144
	v_ashrrev_i32_e32 v153, 31, v152
	v_ashrrev_i32_e32 v155, 31, v154
	v_lshl_add_u32 v220, v152, 10, v154
	v_lshlrev_b32_e32 v220, 2, v220
	v_mov_b32_e32 v204, v220
	v_add_u32_e32 v205, 0x10000, v220
	v_add_u32_e32 v206, 0x20000, v220
	v_add_u32_e32 v207, 0x30000, v220
	v_lshl_add_u32 v208, s12, 0, v220
	v_lshl_add_u32 v209, s14, 0, v220
	v_lshl_add_u32 v210, s18, 0, v220
	v_lshl_add_u32 v211, s20, 0, v220
	s_andn2_b64 vcc, exec, s[2:3]
	s_mov_b64 s[2:3], -1
	global_load_dwordx4 v[168:171], v206, s[52:53]
	global_load_dwordx4 v[172:175], v206, s[52:53] offset:64
	global_load_dwordx4 v[176:179], v206, s[52:53] offset:512
	global_load_dwordx4 v[180:183], v206, s[52:53] offset:576
	global_load_dwordx4 v[184:187], v207, s[52:53]
	global_load_dwordx4 v[188:191], v207, s[52:53] offset:64
	global_load_dwordx4 v[192:195], v207, s[52:53] offset:512
	global_load_dwordx4 v[196:199], v207, s[52:53] offset:576
	s_waitcnt vmcnt(8)
	v_fma_f32 v124, v222, s10, v124
	v_fma_f32 v125, v223, s10, v125
	v_fma_f32 v126, v224, s10, v126
	v_fma_f32 v127, v225, s10, v127
	global_store_dwordx4 v204, v[124:127], s[24:25]
	s_waitcnt vmcnt(9)
	v_fma_f32 v120, v226, s10, v120
	v_fma_f32 v121, v227, s10, v121
	v_fma_f32 v122, v228, s10, v122
	v_fma_f32 v123, v229, s10, v123
	global_store_dwordx4 v204, v[120:123], s[24:25] offset:64
	s_waitcnt vmcnt(10)
	v_fma_f32 v116, v230, s10, v116
	v_fma_f32 v117, v231, s10, v117
	v_fma_f32 v118, v232, s10, v118
	v_fma_f32 v119, v233, s10, v119
	global_store_dwordx4 v204, v[116:119], s[24:25] offset:512
	s_waitcnt vmcnt(11)
	v_fma_f32 v104, v234, s10, v104
	v_fma_f32 v105, v235, s10, v105
	v_fma_f32 v106, v236, s10, v106
	v_fma_f32 v107, v237, s10, v107
	global_store_dwordx4 v204, v[104:107], s[24:25] offset:576
	s_waitcnt vmcnt(12)
	v_fma_f32 v112, v238, s10, v112
	v_fma_f32 v113, v239, s10, v113
	v_fma_f32 v114, v240, s10, v114
	v_fma_f32 v115, v241, s10, v115
	global_store_dwordx4 v205, v[112:115], s[24:25]
	s_waitcnt vmcnt(13)
	v_fma_f32 v108, v242, s10, v108
	v_fma_f32 v109, v243, s10, v109
	v_fma_f32 v110, v244, s10, v110
	v_fma_f32 v111, v245, s10, v111
	global_store_dwordx4 v205, v[108:111], s[24:25] offset:64
	s_waitcnt vmcnt(14)
	v_fma_f32 v100, v246, s10, v100
	v_fma_f32 v101, v247, s10, v101
	v_fma_f32 v102, v248, s10, v102
	v_fma_f32 v103, v249, s10, v103
	global_store_dwordx4 v205, v[100:103], s[24:25] offset:512
	s_waitcnt vmcnt(15)
	v_fma_f32 v88, v250, s10, v88
	v_fma_f32 v89, v251, s10, v89
	v_fma_f32 v90, v252, s10, v90
	v_fma_f32 v91, v253, s10, v91
	global_store_dwordx4 v205, v[88:91], s[24:25] offset:576
	s_waitcnt vmcnt(15)
	v_fma_f32 v96, v168, s10, v96
	v_fma_f32 v97, v169, s10, v97
	v_fma_f32 v98, v170, s10, v98
	v_fma_f32 v99, v171, s10, v99
	global_store_dwordx4 v206, v[96:99], s[24:25]
	global_load_dwordx4 v[168:171], v208, s[52:53]
	s_waitcnt vmcnt(16)
	v_fma_f32 v92, v172, s10, v92
	v_fma_f32 v93, v173, s10, v93
	v_fma_f32 v94, v174, s10, v94
	v_fma_f32 v95, v175, s10, v95
	global_store_dwordx4 v206, v[92:95], s[24:25] offset:64
	global_load_dwordx4 v[172:175], v208, s[52:53] offset:64
	s_waitcnt vmcnt(17)
	v_fma_f32 v84, v176, s10, v84
	v_fma_f32 v85, v177, s10, v85
	v_fma_f32 v86, v178, s10, v86
	v_fma_f32 v87, v179, s10, v87
	global_store_dwordx4 v206, v[84:87], s[24:25] offset:512
	global_load_dwordx4 v[176:179], v208, s[52:53] offset:512
	s_waitcnt vmcnt(18)
	v_fma_f32 v72, v180, s10, v72
	v_fma_f32 v73, v181, s10, v73
	v_fma_f32 v74, v182, s10, v74
	v_fma_f32 v75, v183, s10, v75
	global_store_dwordx4 v206, v[72:75], s[24:25] offset:576
	global_load_dwordx4 v[180:183], v208, s[52:53] offset:576
	s_waitcnt vmcnt(19)
	v_fma_f32 v80, v184, s10, v80
	v_fma_f32 v81, v185, s10, v81
	v_fma_f32 v82, v186, s10, v82
	v_fma_f32 v83, v187, s10, v83
	global_store_dwordx4 v207, v[80:83], s[24:25]
	global_load_dwordx4 v[184:187], v209, s[52:53]
	s_waitcnt vmcnt(20)
	v_fma_f32 v76, v188, s10, v76
	v_fma_f32 v77, v189, s10, v77
	v_fma_f32 v78, v190, s10, v78
	v_fma_f32 v79, v191, s10, v79
	global_store_dwordx4 v207, v[76:79], s[24:25] offset:64
	global_load_dwordx4 v[188:191], v209, s[52:53] offset:64
	s_waitcnt vmcnt(21)
	v_fma_f32 v68, v192, s10, v68
	v_fma_f32 v69, v193, s10, v69
	v_fma_f32 v70, v194, s10, v70
	v_fma_f32 v71, v195, s10, v71
	global_store_dwordx4 v207, v[68:71], s[24:25] offset:512
	global_load_dwordx4 v[192:195], v209, s[52:53] offset:512
	s_waitcnt vmcnt(22)
	v_fma_f32 v64, v196, s10, v64
	v_fma_f32 v65, v197, s10, v65
	v_fma_f32 v66, v198, s10, v66
	v_fma_f32 v67, v199, s10, v67
	global_store_dwordx4 v207, v[64:67], s[24:25] offset:576
	global_load_dwordx4 v[196:199], v209, s[52:53] offset:576
	s_waitcnt vmcnt(14)
	v_fma_f32 v60, v168, s10, v60
	v_fma_f32 v61, v169, s10, v61
	v_fma_f32 v62, v170, s10, v62
	v_fma_f32 v63, v171, s10, v63
	global_store_dwordx4 v208, v[60:63], s[24:25]
	global_load_dwordx4 v[168:171], v210, s[52:53]
	s_waitcnt vmcnt(14)
	v_fma_f32 v56, v172, s10, v56
	v_fma_f32 v57, v173, s10, v57
	v_fma_f32 v58, v174, s10, v58
	v_fma_f32 v59, v175, s10, v59
	global_store_dwordx4 v208, v[56:59], s[24:25] offset:64
	global_load_dwordx4 v[172:175], v210, s[52:53] offset:64
	s_waitcnt vmcnt(14)
	v_fma_f32 v52, v176, s10, v52
	v_fma_f32 v53, v177, s10, v53
	v_fma_f32 v54, v178, s10, v54
	v_fma_f32 v55, v179, s10, v55
	global_store_dwordx4 v208, v[52:55], s[24:25] offset:512
	global_load_dwordx4 v[176:179], v210, s[52:53] offset:512
	s_waitcnt vmcnt(14)
	v_fma_f32 v40, v180, s10, v40
	v_fma_f32 v41, v181, s10, v41
	v_fma_f32 v42, v182, s10, v42
	v_fma_f32 v43, v183, s10, v43
	global_store_dwordx4 v208, v[40:43], s[24:25] offset:576
	global_load_dwordx4 v[180:183], v210, s[52:53] offset:576
	s_waitcnt vmcnt(14)
	v_fma_f32 v48, v184, s10, v48
	v_fma_f32 v49, v185, s10, v49
	v_fma_f32 v50, v186, s10, v50
	v_fma_f32 v51, v187, s10, v51
	global_store_dwordx4 v209, v[48:51], s[24:25]
	global_load_dwordx4 v[184:187], v211, s[52:53]
	s_waitcnt vmcnt(14)
	v_fma_f32 v44, v188, s10, v44
	v_fma_f32 v45, v189, s10, v45
	v_fma_f32 v46, v190, s10, v46
	v_fma_f32 v47, v191, s10, v47
	global_store_dwordx4 v209, v[44:47], s[24:25] offset:64
	global_load_dwordx4 v[188:191], v211, s[52:53] offset:64
	s_waitcnt vmcnt(14)
	v_fma_f32 v36, v192, s10, v36
	v_fma_f32 v37, v193, s10, v37
	v_fma_f32 v38, v194, s10, v38
	v_fma_f32 v39, v195, s10, v39
	global_store_dwordx4 v209, v[36:39], s[24:25] offset:512
	global_load_dwordx4 v[192:195], v211, s[52:53] offset:512
	s_waitcnt vmcnt(14)
	v_fma_f32 v24, v196, s10, v24
	v_fma_f32 v25, v197, s10, v25
	v_fma_f32 v26, v198, s10, v26
	v_fma_f32 v27, v199, s10, v27
	global_store_dwordx4 v209, v[24:27], s[24:25] offset:576
	global_load_dwordx4 v[196:199], v211, s[52:53] offset:576
	s_waitcnt vmcnt(14)
	v_fma_f32 v32, v168, s10, v32
	v_fma_f32 v33, v169, s10, v33
	v_fma_f32 v34, v170, s10, v34
	v_fma_f32 v35, v171, s10, v35
	global_store_dwordx4 v210, v[32:35], s[24:25]
	s_waitcnt vmcnt(13)
	v_fma_f32 v28, v172, s10, v28
	v_fma_f32 v29, v173, s10, v29
	v_fma_f32 v30, v174, s10, v30
	v_fma_f32 v31, v175, s10, v31
	global_store_dwordx4 v210, v[28:31], s[24:25] offset:64
	s_waitcnt vmcnt(12)
	v_fma_f32 v20, v176, s10, v20
	v_fma_f32 v21, v177, s10, v21
	v_fma_f32 v22, v178, s10, v22
	v_fma_f32 v23, v179, s10, v23
	global_store_dwordx4 v210, v[20:23], s[24:25] offset:512
	s_waitcnt vmcnt(11)
	v_fma_f32 v8, v180, s10, v8
	v_fma_f32 v9, v181, s10, v9
	v_fma_f32 v10, v182, s10, v10
	v_fma_f32 v11, v183, s10, v11
	global_store_dwordx4 v210, v[8:11], s[24:25] offset:576
	s_waitcnt vmcnt(10)
	v_fma_f32 v16, v184, s10, v16
	v_fma_f32 v17, v185, s10, v17
	v_fma_f32 v18, v186, s10, v18
	v_fma_f32 v19, v187, s10, v19
	global_store_dwordx4 v211, v[16:19], s[24:25]
	s_waitcnt vmcnt(9)
	v_fma_f32 v12, v188, s10, v12
	v_fma_f32 v13, v189, s10, v13
	v_fma_f32 v14, v190, s10, v14
	v_fma_f32 v15, v191, s10, v15
	global_store_dwordx4 v211, v[12:15], s[24:25] offset:64
	s_waitcnt vmcnt(8)
	v_fma_f32 v4, v192, s10, v4
	v_fma_f32 v5, v193, s10, v5
	v_fma_f32 v6, v194, s10, v6
	v_fma_f32 v7, v195, s10, v7
	global_store_dwordx4 v211, v[4:7], s[24:25] offset:512
	s_waitcnt vmcnt(7)
	v_fma_f32 v0, v196, s10, v0
	v_fma_f32 v1, v197, s10, v1
	v_fma_f32 v2, v198, s10, v2
	v_fma_f32 v3, v199, s10, v3
	global_store_dwordx4 v211, v[0:3], s[24:25] offset:576
	s_cbranch_vccnz .LBB0_725
	s_andn2_b64 vcc, exec, s[4:5]
	s_cbranch_vccnz .LBB0_724
	s_barrier
	s_branch .LBB0_724

.LBB0_1017:
	s_add_u32 s52, s52, 0xb0080
	s_addc_u32 s53, s53, 0
	s_add_u32 s76, s54, 0x100
	s_addc_u32 s77, s55, 0
	s_mov_b32 s78, -2
	v_mov_b64_e32 v[0:1], 0
	v_mov_b64_e32 v[2:3], 0
	v_mov_b64_e32 v[4:5], 0
	v_mov_b64_e32 v[6:7], 0
	v_mov_b64_e32 v[8:9], 0
	v_mov_b64_e32 v[10:11], 0
	v_mov_b64_e32 v[12:13], 0
	v_mov_b64_e32 v[14:15], 0
	v_mov_b64_e32 v[16:17], 0
	v_mov_b64_e32 v[18:19], 0
	v_mov_b64_e32 v[20:21], 0
	v_mov_b64_e32 v[22:23], 0
	v_mov_b64_e32 v[24:25], 0
	v_mov_b64_e32 v[26:27], 0
	v_mov_b64_e32 v[28:29], 0
	v_mov_b64_e32 v[30:31], 0
	v_mov_b64_e32 v[32:33], 0
	v_mov_b64_e32 v[34:35], 0
	v_mov_b64_e32 v[36:37], 0
	v_mov_b64_e32 v[38:39], 0
	v_mov_b64_e32 v[40:41], 0
	v_mov_b64_e32 v[42:43], 0
	v_mov_b64_e32 v[44:45], 0
	v_mov_b64_e32 v[46:47], 0
	v_mov_b64_e32 v[48:49], 0
	v_mov_b64_e32 v[50:51], 0
	v_mov_b64_e32 v[52:53], 0
	v_mov_b64_e32 v[54:55], 0
	v_mov_b64_e32 v[56:57], 0
	v_mov_b64_e32 v[58:59], 0
	v_mov_b64_e32 v[60:61], 0
	v_mov_b64_e32 v[62:63], 0
	v_mov_b64_e32 v[64:65], 0
	v_mov_b64_e32 v[66:67], 0
	v_mov_b64_e32 v[68:69], 0
	v_mov_b64_e32 v[70:71], 0
	v_mov_b64_e32 v[72:73], 0
	v_mov_b64_e32 v[74:75], 0
	v_mov_b64_e32 v[76:77], 0
	v_mov_b64_e32 v[78:79], 0
	v_mov_b64_e32 v[80:81], 0
	v_mov_b64_e32 v[82:83], 0
	v_mov_b64_e32 v[84:85], 0
	v_mov_b64_e32 v[86:87], 0
	v_mov_b64_e32 v[88:89], 0
	v_mov_b64_e32 v[90:91], 0
	v_mov_b64_e32 v[92:93], 0
	v_mov_b64_e32 v[94:95], 0
	v_mov_b64_e32 v[96:97], 0
	v_mov_b64_e32 v[98:99], 0
	v_mov_b64_e32 v[100:101], 0
	v_mov_b64_e32 v[102:103], 0
	v_mov_b64_e32 v[104:105], 0
	v_mov_b64_e32 v[106:107], 0
	v_mov_b64_e32 v[108:109], 0
	v_mov_b64_e32 v[110:111], 0
	v_mov_b64_e32 v[112:113], 0
	v_mov_b64_e32 v[114:115], 0
	v_mov_b64_e32 v[116:117], 0
	v_mov_b64_e32 v[118:119], 0
	v_mov_b64_e32 v[120:121], 0
	v_mov_b64_e32 v[122:123], 0
	v_mov_b64_e32 v[124:125], 0
	v_mov_b64_e32 v[126:127], 0
	v_lshl_add_u32 v160, s1, 8, v146
	v_lshl_or_b32 v161, s0, 8, v148
	v_lshl_add_u32 v160, v160, 10, v161
	v_lshlrev_b32_e32 v160, 2, v160
	v_mov_b32_e32 v161, v160
	v_add_u32_e32 v162, 0x10000, v160
	v_add_u32_e32 v163, 0x20000, v160
	v_add_u32_e32 v164, 0x30000, v160
	v_lshrrev_b32_e32 v161, 1, v161
	v_lshrrev_b32_e32 v162, 1, v162
	v_lshrrev_b32_e32 v163, 1, v163
	v_lshrrev_b32_e32 v164, 1, v164
	global_load_dwordx2 v[222:223], v161, s[8:9]
	global_load_dwordx2 v[224:225], v161, s[8:9] offset:32
	global_load_dwordx2 v[226:227], v161, s[8:9] offset:256
	global_load_dwordx2 v[228:229], v161, s[8:9] offset:288
	global_load_dwordx2 v[230:231], v162, s[8:9]
	global_load_dwordx2 v[232:233], v162, s[8:9] offset:32
	global_load_dwordx2 v[234:235], v162, s[8:9] offset:256
	global_load_dwordx2 v[236:237], v162, s[8:9] offset:288
	global_load_dwordx2 v[238:239], v163, s[8:9]
	global_load_dwordx2 v[240:241], v163, s[8:9] offset:32
	global_load_dwordx2 v[242:243], v163, s[8:9] offset:256
	global_load_dwordx2 v[244:245], v163, s[8:9] offset:288
	global_load_dwordx2 v[246:247], v164, s[8:9]
	global_load_dwordx2 v[248:249], v164, s[8:9] offset:32
	global_load_dwordx2 v[250:251], v164, s[8:9] offset:256
	global_load_dwordx2 v[252:253], v164, s[8:9] offset:288

.LBB0_1021:
	v_lshl_add_u32 v144, s1, 8, v146
	v_lshl_or_b32 v142, s0, 8, v148
	v_ashrrev_i32_e32 v145, 31, v144
	v_ashrrev_i32_e32 v143, 31, v142
	v_lshl_add_u32 v220, v144, 10, v142
	v_lshlrev_b32_e32 v220, 2, v220
	v_mov_b32_e32 v204, v220
	v_lshrrev_b32_e32 v212, 1, v204
	v_add_u32_e32 v205, 0x10000, v220
	v_lshrrev_b32_e32 v213, 1, v205
	v_add_u32_e32 v206, 0x20000, v220
	v_lshrrev_b32_e32 v214, 1, v206
	v_add_u32_e32 v207, 0x30000, v220
	v_lshrrev_b32_e32 v215, 1, v207
	v_lshl_add_u32 v208, s18, 2, v220
	v_lshrrev_b32_e32 v216, 1, v208
	v_lshl_add_u32 v209, s20, 2, v220
	v_lshrrev_b32_e32 v217, 1, v209
	v_lshl_add_u32 v210, s34, 2, v220
	v_lshrrev_b32_e32 v218, 1, v210
	v_lshl_add_u32 v211, s44, 2, v220
	v_lshrrev_b32_e32 v219, 1, v211
	s_and_b64 vcc, exec, s[2:3]
	s_mov_b64 s[2:3], -1
	global_load_dwordx2 v[168:169], v216, s[8:9]
	global_load_dwordx2 v[170:171], v216, s[8:9] offset:32
	global_load_dwordx2 v[172:173], v216, s[8:9] offset:256
	global_load_dwordx2 v[174:175], v216, s[8:9] offset:288
	global_load_dwordx2 v[176:177], v217, s[8:9]
	global_load_dwordx2 v[178:179], v217, s[8:9] offset:32
	global_load_dwordx2 v[180:181], v217, s[8:9] offset:256
	global_load_dwordx2 v[182:183], v217, s[8:9] offset:288
	global_load_dwordx2 v[184:185], v218, s[8:9]
	global_load_dwordx2 v[186:187], v218, s[8:9] offset:32
	global_load_dwordx2 v[188:189], v218, s[8:9] offset:256
	global_load_dwordx2 v[190:191], v218, s[8:9] offset:288
	global_load_dwordx2 v[192:193], v219, s[8:9]
	global_load_dwordx2 v[194:195], v219, s[8:9] offset:32
	global_load_dwordx2 v[196:197], v219, s[8:9] offset:256
	global_load_dwordx2 v[198:199], v219, s[8:9] offset:288
	s_waitcnt vmcnt(16)
	v_lshlrev_b32_e32 v220, 16, v222
	v_and_b32_e32 v222, 0xffff0000, v222
	v_lshlrev_b32_e32 v221, 16, v223
	v_and_b32_e32 v223, 0xffff0000, v223
	v_fma_f32 v124, v220, s14, v124
	v_fma_f32 v125, v222, s14, v125
	v_fma_f32 v126, v221, s14, v126
	v_fma_f32 v127, v223, s14, v127
	global_store_dwordx4 v204, v[124:127], s[24:25]
	s_waitcnt vmcnt(17)
	v_lshlrev_b32_e32 v220, 16, v224
	v_and_b32_e32 v224, 0xffff0000, v224
	v_lshlrev_b32_e32 v221, 16, v225
	v_and_b32_e32 v225, 0xffff0000, v225
	v_fma_f32 v120, v220, s14, v120
	v_fma_f32 v121, v224, s14, v121
	v_fma_f32 v122, v221, s14, v122
	v_fma_f32 v123, v225, s14, v123
	global_store_dwordx4 v204, v[120:123], s[24:25] offset:64
	s_waitcnt vmcnt(18)
	v_lshlrev_b32_e32 v220, 16, v226
	v_and_b32_e32 v226, 0xffff0000, v226
	v_lshlrev_b32_e32 v221, 16, v227
	v_and_b32_e32 v227, 0xffff0000, v227
	v_fma_f32 v116, v220, s14, v116
	v_fma_f32 v117, v226, s14, v117
	v_fma_f32 v118, v221, s14, v118
	v_fma_f32 v119, v227, s14, v119
	global_store_dwordx4 v204, v[116:119], s[24:25] offset:512
	s_waitcnt vmcnt(19)
	v_lshlrev_b32_e32 v220, 16, v228
	v_and_b32_e32 v228, 0xffff0000, v228
	v_lshlrev_b32_e32 v221, 16, v229
	v_and_b32_e32 v229, 0xffff0000, v229
	v_fma_f32 v108, v220, s14, v108
	v_fma_f32 v109, v228, s14, v109
	v_fma_f32 v110, v221, s14, v110
	v_fma_f32 v111, v229, s14, v111
	global_store_dwordx4 v204, v[108:111], s[24:25] offset:576
	s_waitcnt vmcnt(20)
	v_lshlrev_b32_e32 v220, 16, v230
	v_and_b32_e32 v230, 0xffff0000, v230
	v_lshlrev_b32_e32 v221, 16, v231
	v_and_b32_e32 v231, 0xffff0000, v231
	v_fma_f32 v112, v220, s14, v112
	v_fma_f32 v113, v230, s14, v113
	v_fma_f32 v114, v221, s14, v114
	v_fma_f32 v115, v231, s14, v115
	global_store_dwordx4 v205, v[112:115], s[24:25]
	s_waitcnt vmcnt(21)
	v_lshlrev_b32_e32 v220, 16, v232
	v_and_b32_e32 v232, 0xffff0000, v232
	v_lshlrev_b32_e32 v221, 16, v233
	v_and_b32_e32 v233, 0xffff0000, v233
	v_fma_f32 v104, v220, s14, v104
	v_fma_f32 v105, v232, s14, v105
	v_fma_f32 v106, v221, s14, v106
	v_fma_f32 v107, v233, s14, v107
	global_store_dwordx4 v205, v[104:107], s[24:25] offset:64
	s_waitcnt vmcnt(22)
	v_lshlrev_b32_e32 v220, 16, v234
	v_and_b32_e32 v234, 0xffff0000, v234
	v_lshlrev_b32_e32 v221, 16, v235
	v_and_b32_e32 v235, 0xffff0000, v235
	v_fma_f32 v100, v220, s14, v100
	v_fma_f32 v101, v234, s14, v101
	v_fma_f32 v102, v221, s14, v102
	v_fma_f32 v103, v235, s14, v103
	global_store_dwordx4 v205, v[100:103], s[24:25] offset:512
	s_waitcnt vmcnt(23)
	v_lshlrev_b32_e32 v220, 16, v236
	v_and_b32_e32 v236, 0xffff0000, v236
	v_lshlrev_b32_e32 v221, 16, v237
	v_and_b32_e32 v237, 0xffff0000, v237
	v_fma_f32 v92, v220, s14, v92
	v_fma_f32 v93, v236, s14, v93
	v_fma_f32 v94, v221, s14, v94
	v_fma_f32 v95, v237, s14, v95
	global_store_dwordx4 v205, v[92:95], s[24:25] offset:576
	s_waitcnt vmcnt(24)
	v_lshlrev_b32_e32 v220, 16, v238
	v_and_b32_e32 v238, 0xffff0000, v238
	v_lshlrev_b32_e32 v221, 16, v239
	v_and_b32_e32 v239, 0xffff0000, v239
	v_fma_f32 v96, v220, s14, v96
	v_fma_f32 v97, v238, s14, v97
	v_fma_f32 v98, v221, s14, v98
	v_fma_f32 v99, v239, s14, v99
	global_store_dwordx4 v206, v[96:99], s[24:25]
	s_waitcnt vmcnt(25)
	v_lshlrev_b32_e32 v220, 16, v240
	v_and_b32_e32 v240, 0xffff0000, v240
	v_lshlrev_b32_e32 v221, 16, v241
	v_and_b32_e32 v241, 0xffff0000, v241
	v_fma_f32 v88, v220, s14, v88
	v_fma_f32 v89, v240, s14, v89
	v_fma_f32 v90, v221, s14, v90
	v_fma_f32 v91, v241, s14, v91
	global_store_dwordx4 v206, v[88:91], s[24:25] offset:64
	s_waitcnt vmcnt(26)
	v_lshlrev_b32_e32 v220, 16, v242
	v_and_b32_e32 v242, 0xffff0000, v242
	v_lshlrev_b32_e32 v221, 16, v243
	v_and_b32_e32 v243, 0xffff0000, v243
	v_fma_f32 v84, v220, s14, v84
	v_fma_f32 v85, v242, s14, v85
	v_fma_f32 v86, v221, s14, v86
	v_fma_f32 v87, v243, s14, v87
	global_store_dwordx4 v206, v[84:87], s[24:25] offset:512
	s_waitcnt vmcnt(27)
	v_lshlrev_b32_e32 v220, 16, v244
	v_and_b32_e32 v244, 0xffff0000, v244
	v_lshlrev_b32_e32 v221, 16, v245
	v_and_b32_e32 v245, 0xffff0000, v245
	v_fma_f32 v76, v220, s14, v76
	v_fma_f32 v77, v244, s14, v77
	v_fma_f32 v78, v221, s14, v78
	v_fma_f32 v79, v245, s14, v79
	global_store_dwordx4 v206, v[76:79], s[24:25] offset:576
	s_waitcnt vmcnt(28)
	v_lshlrev_b32_e32 v220, 16, v246
	v_and_b32_e32 v246, 0xffff0000, v246
	v_lshlrev_b32_e32 v221, 16, v247
	v_and_b32_e32 v247, 0xffff0000, v247
	v_fma_f32 v80, v220, s14, v80
	v_fma_f32 v81, v246, s14, v81
	v_fma_f32 v82, v221, s14, v82
	v_fma_f32 v83, v247, s14, v83
	global_store_dwordx4 v207, v[80:83], s[24:25]
	s_waitcnt vmcnt(29)
	v_lshlrev_b32_e32 v220, 16, v248
	v_and_b32_e32 v248, 0xffff0000, v248
	v_lshlrev_b32_e32 v221, 16, v249
	v_and_b32_e32 v249, 0xffff0000, v249
	v_fma_f32 v72, v220, s14, v72
	v_fma_f32 v73, v248, s14, v73
	v_fma_f32 v74, v221, s14, v74
	v_fma_f32 v75, v249, s14, v75
	global_store_dwordx4 v207, v[72:75], s[24:25] offset:64
	s_waitcnt vmcnt(30)
	v_lshlrev_b32_e32 v220, 16, v250
	v_and_b32_e32 v250, 0xffff0000, v250
	v_lshlrev_b32_e32 v221, 16, v251
	v_and_b32_e32 v251, 0xffff0000, v251
	v_fma_f32 v68, v220, s14, v68
	v_fma_f32 v69, v250, s14, v69
	v_fma_f32 v70, v221, s14, v70
	v_fma_f32 v71, v251, s14, v71
	global_store_dwordx4 v207, v[68:71], s[24:25] offset:512
	s_waitcnt vmcnt(31)
	v_lshlrev_b32_e32 v220, 16, v252
	v_and_b32_e32 v252, 0xffff0000, v252
	v_lshlrev_b32_e32 v221, 16, v253
	v_and_b32_e32 v253, 0xffff0000, v253
	v_fma_f32 v64, v220, s14, v64
	v_fma_f32 v65, v252, s14, v65
	v_fma_f32 v66, v221, s14, v66
	v_fma_f32 v67, v253, s14, v67
	global_store_dwordx4 v207, v[64:67], s[24:25] offset:576
	s_waitcnt vmcnt(31)
	v_lshlrev_b32_e32 v220, 16, v168
	v_and_b32_e32 v168, 0xffff0000, v168
	v_lshlrev_b32_e32 v221, 16, v169
	v_and_b32_e32 v169, 0xffff0000, v169
	v_fma_f32 v60, v220, s14, v60
	v_fma_f32 v61, v168, s14, v61
	v_fma_f32 v62, v221, s14, v62
	v_fma_f32 v63, v169, s14, v63
	global_store_dwordx4 v208, v[60:63], s[24:25]
	s_waitcnt vmcnt(31)
	v_lshlrev_b32_e32 v220, 16, v170
	v_and_b32_e32 v170, 0xffff0000, v170
	v_lshlrev_b32_e32 v221, 16, v171
	v_and_b32_e32 v171, 0xffff0000, v171
	v_fma_f32 v56, v220, s14, v56
	v_fma_f32 v57, v170, s14, v57
	v_fma_f32 v58, v221, s14, v58
	v_fma_f32 v59, v171, s14, v59
	global_store_dwordx4 v208, v[56:59], s[24:25] offset:64
	s_waitcnt vmcnt(31)
	v_lshlrev_b32_e32 v220, 16, v172
	v_and_b32_e32 v172, 0xffff0000, v172
	v_lshlrev_b32_e32 v221, 16, v173
	v_and_b32_e32 v173, 0xffff0000, v173
	v_fma_f32 v52, v220, s14, v52
	v_fma_f32 v53, v172, s14, v53
	v_fma_f32 v54, v221, s14, v54
	v_fma_f32 v55, v173, s14, v55
	global_store_dwordx4 v208, v[52:55], s[24:25] offset:512
	s_waitcnt vmcnt(31)
	v_lshlrev_b32_e32 v220, 16, v174
	v_and_b32_e32 v174, 0xffff0000, v174
	v_lshlrev_b32_e32 v221, 16, v175
	v_and_b32_e32 v175, 0xffff0000, v175
	v_fma_f32 v44, v220, s14, v44
	v_fma_f32 v45, v174, s14, v45
	v_fma_f32 v46, v221, s14, v46
	v_fma_f32 v47, v175, s14, v47
	global_store_dwordx4 v208, v[44:47], s[24:25] offset:576
	s_waitcnt vmcnt(31)
	v_lshlrev_b32_e32 v220, 16, v176
	v_and_b32_e32 v176, 0xffff0000, v176
	v_lshlrev_b32_e32 v221, 16, v177
	v_and_b32_e32 v177, 0xffff0000, v177
	v_fma_f32 v48, v220, s14, v48
	v_fma_f32 v49, v176, s14, v49
	v_fma_f32 v50, v221, s14, v50
	v_fma_f32 v51, v177, s14, v51
	global_store_dwordx4 v209, v[48:51], s[24:25]
	s_waitcnt vmcnt(31)
	v_lshlrev_b32_e32 v220, 16, v178
	v_and_b32_e32 v178, 0xffff0000, v178
	v_lshlrev_b32_e32 v221, 16, v179
	v_and_b32_e32 v179, 0xffff0000, v179
	v_fma_f32 v40, v220, s14, v40
	v_fma_f32 v41, v178, s14, v41
	v_fma_f32 v42, v221, s14, v42
	v_fma_f32 v43, v179, s14, v43
	global_store_dwordx4 v209, v[40:43], s[24:25] offset:64
	s_waitcnt vmcnt(31)
	v_lshlrev_b32_e32 v220, 16, v180
	v_and_b32_e32 v180, 0xffff0000, v180
	v_lshlrev_b32_e32 v221, 16, v181
	v_and_b32_e32 v181, 0xffff0000, v181
	v_fma_f32 v36, v220, s14, v36
	v_fma_f32 v37, v180, s14, v37
	v_fma_f32 v38, v221, s14, v38
	v_fma_f32 v39, v181, s14, v39
	global_store_dwordx4 v209, v[36:39], s[24:25] offset:512
	s_waitcnt vmcnt(31)
	v_lshlrev_b32_e32 v220, 16, v182
	v_and_b32_e32 v182, 0xffff0000, v182
	v_lshlrev_b32_e32 v221, 16, v183
	v_and_b32_e32 v183, 0xffff0000, v183
	v_fma_f32 v28, v220, s14, v28
	v_fma_f32 v29, v182, s14, v29
	v_fma_f32 v30, v221, s14, v30
	v_fma_f32 v31, v183, s14, v31
	global_store_dwordx4 v209, v[28:31], s[24:25] offset:576
	s_waitcnt vmcnt(31)
	v_lshlrev_b32_e32 v220, 16, v184
	v_and_b32_e32 v184, 0xffff0000, v184
	v_lshlrev_b32_e32 v221, 16, v185
	v_and_b32_e32 v185, 0xffff0000, v185
	v_fma_f32 v32, v220, s14, v32
	v_fma_f32 v33, v184, s14, v33
	v_fma_f32 v34, v221, s14, v34
	v_fma_f32 v35, v185, s14, v35
	global_store_dwordx4 v210, v[32:35], s[24:25]
	s_waitcnt vmcnt(31)
	v_lshlrev_b32_e32 v220, 16, v186
	v_and_b32_e32 v186, 0xffff0000, v186
	v_lshlrev_b32_e32 v221, 16, v187
	v_and_b32_e32 v187, 0xffff0000, v187
	v_fma_f32 v24, v220, s14, v24
	v_fma_f32 v25, v186, s14, v25
	v_fma_f32 v26, v221, s14, v26
	v_fma_f32 v27, v187, s14, v27
	global_store_dwordx4 v210, v[24:27], s[24:25] offset:64
	s_waitcnt vmcnt(31)
	v_lshlrev_b32_e32 v220, 16, v188
	v_and_b32_e32 v188, 0xffff0000, v188
	v_lshlrev_b32_e32 v221, 16, v189
	v_and_b32_e32 v189, 0xffff0000, v189
	v_fma_f32 v20, v220, s14, v20
	v_fma_f32 v21, v188, s14, v21
	v_fma_f32 v22, v221, s14, v22
	v_fma_f32 v23, v189, s14, v23
	global_store_dwordx4 v210, v[20:23], s[24:25] offset:512
	s_waitcnt vmcnt(31)
	v_lshlrev_b32_e32 v220, 16, v190
	v_and_b32_e32 v190, 0xffff0000, v190
	v_lshlrev_b32_e32 v221, 16, v191
	v_and_b32_e32 v191, 0xffff0000, v191
	v_fma_f32 v12, v220, s14, v12
	v_fma_f32 v13, v190, s14, v13
	v_fma_f32 v14, v221, s14, v14
	v_fma_f32 v15, v191, s14, v15
	global_store_dwordx4 v210, v[12:15], s[24:25] offset:576
	s_waitcnt vmcnt(31)
	v_lshlrev_b32_e32 v220, 16, v192
	v_and_b32_e32 v192, 0xffff0000, v192
	v_lshlrev_b32_e32 v221, 16, v193
	v_and_b32_e32 v193, 0xffff0000, v193
	v_fma_f32 v16, v220, s14, v16
	v_fma_f32 v17, v192, s14, v17
	v_fma_f32 v18, v221, s14, v18
	v_fma_f32 v19, v193, s14, v19
	global_store_dwordx4 v211, v[16:19], s[24:25]
	s_waitcnt vmcnt(31)
	v_lshlrev_b32_e32 v220, 16, v194
	v_and_b32_e32 v194, 0xffff0000, v194
	v_lshlrev_b32_e32 v221, 16, v195
	v_and_b32_e32 v195, 0xffff0000, v195
	v_fma_f32 v8, v220, s14, v8
	v_fma_f32 v9, v194, s14, v9
	v_fma_f32 v10, v221, s14, v10
	v_fma_f32 v11, v195, s14, v11
	global_store_dwordx4 v211, v[8:11], s[24:25] offset:64
	s_waitcnt vmcnt(31)
	v_lshlrev_b32_e32 v220, 16, v196
	v_and_b32_e32 v196, 0xffff0000, v196
	v_lshlrev_b32_e32 v221, 16, v197
	v_and_b32_e32 v197, 0xffff0000, v197
	v_fma_f32 v4, v220, s14, v4
	v_fma_f32 v5, v196, s14, v5
	v_fma_f32 v6, v221, s14, v6
	v_fma_f32 v7, v197, s14, v7
	global_store_dwordx4 v211, v[4:7], s[24:25] offset:512
	s_waitcnt vmcnt(31)
	v_lshlrev_b32_e32 v220, 16, v198
	v_and_b32_e32 v198, 0xffff0000, v198
	v_lshlrev_b32_e32 v221, 16, v199
	v_and_b32_e32 v199, 0xffff0000, v199
	v_fma_f32 v0, v220, s14, v0
	v_fma_f32 v1, v198, s14, v1
	v_fma_f32 v2, v221, s14, v2
	v_fma_f32 v3, v199, s14, v3
	global_store_dwordx4 v211, v[0:3], s[24:25] offset:576
	s_cbranch_vccnz .LBB0_1010
	s_andn2_b64 vcc, exec, s[6:7]
	s_cbranch_vccnz .LBB0_1009
	s_barrier
	s_branch .LBB0_1009

.LBB0_1414:
	s_ashr_i32 s51, s50, 31
	s_lshl_b64 s[52:53], s[50:51], 19
	s_add_u32 s52, s13, s52
	s_addc_u32 s53, s17, s53
	s_and_b64 s[54:55], s[2:3], exec
	s_cselect_b32 s51, s53, s57
	s_cselect_b32 s76, s52, s56
	s_ashr_i32 s45, s44, 31
	s_lshl_b64 s[54:55], s[44:45], 19
	s_add_u32 s54, s62, s54
	s_addc_u32 s55, s63, s55
	s_and_b64 s[60:61], s[2:3], exec
	s_cselect_b32 s45, s55, s59
	s_cselect_b32 s77, s54, s58
	s_add_u32 s56, s56, 0x40080
	s_addc_u32 s57, s57, 0
	s_add_u32 s78, s58, 0x100
	s_addc_u32 s79, s59, 0
	s_mov_b32 s80, -2
	v_mov_b64_e32 v[0:1], 0
	v_mov_b64_e32 v[2:3], 0
	v_mov_b64_e32 v[4:5], 0
	v_mov_b64_e32 v[6:7], 0
	v_mov_b64_e32 v[8:9], 0
	v_mov_b64_e32 v[10:11], 0
	v_mov_b64_e32 v[12:13], 0
	v_mov_b64_e32 v[14:15], 0
	v_mov_b64_e32 v[16:17], 0
	v_mov_b64_e32 v[18:19], 0
	v_mov_b64_e32 v[20:21], 0
	v_mov_b64_e32 v[22:23], 0
	v_mov_b64_e32 v[24:25], 0
	v_mov_b64_e32 v[26:27], 0
	v_mov_b64_e32 v[28:29], 0
	v_mov_b64_e32 v[30:31], 0
	v_mov_b64_e32 v[32:33], 0
	v_mov_b64_e32 v[34:35], 0
	v_mov_b64_e32 v[36:37], 0
	v_mov_b64_e32 v[38:39], 0
	v_mov_b64_e32 v[40:41], 0
	v_mov_b64_e32 v[42:43], 0
	v_mov_b64_e32 v[44:45], 0
	v_mov_b64_e32 v[46:47], 0
	v_mov_b64_e32 v[48:49], 0
	v_mov_b64_e32 v[50:51], 0
	v_mov_b64_e32 v[52:53], 0
	v_mov_b64_e32 v[54:55], 0
	v_mov_b64_e32 v[56:57], 0
	v_mov_b64_e32 v[58:59], 0
	v_mov_b64_e32 v[60:61], 0
	v_mov_b64_e32 v[62:63], 0
	v_mov_b64_e32 v[64:65], 0
	v_mov_b64_e32 v[66:67], 0
	v_mov_b64_e32 v[68:69], 0
	v_mov_b64_e32 v[70:71], 0
	v_mov_b64_e32 v[72:73], 0
	v_mov_b64_e32 v[74:75], 0
	v_mov_b64_e32 v[76:77], 0
	v_mov_b64_e32 v[78:79], 0
	v_mov_b64_e32 v[80:81], 0
	v_mov_b64_e32 v[82:83], 0
	v_mov_b64_e32 v[84:85], 0
	v_mov_b64_e32 v[86:87], 0
	v_mov_b64_e32 v[88:89], 0
	v_mov_b64_e32 v[90:91], 0
	v_mov_b64_e32 v[92:93], 0
	v_mov_b64_e32 v[94:95], 0
	v_mov_b64_e32 v[96:97], 0
	v_mov_b64_e32 v[98:99], 0
	v_mov_b64_e32 v[100:101], 0
	v_mov_b64_e32 v[102:103], 0
	v_mov_b64_e32 v[104:105], 0
	v_mov_b64_e32 v[106:107], 0
	v_mov_b64_e32 v[108:109], 0
	v_mov_b64_e32 v[110:111], 0
	v_mov_b64_e32 v[112:113], 0
	v_mov_b64_e32 v[114:115], 0
	v_mov_b64_e32 v[116:117], 0
	v_mov_b64_e32 v[118:119], 0
	v_mov_b64_e32 v[120:121], 0
	v_mov_b64_e32 v[122:123], 0
	v_mov_b64_e32 v[124:125], 0
	v_mov_b64_e32 v[126:127], 0
	s_waitcnt vmcnt(0)
	v_lshl_add_u32 v160, s1, 8, v146
	v_lshl_or_b32 v161, s0, 8, v148
	v_lshl_add_u32 v160, v160, 10, v161
	v_lshlrev_b32_e32 v160, 2, v160
	v_mov_b32_e32 v161, v160
	v_add_u32_e32 v162, 0x10000, v160
	v_add_u32_e32 v163, 0x20000, v160
	v_add_u32_e32 v164, 0x30000, v160
	v_lshrrev_b32_e32 v161, 1, v161
	v_lshrrev_b32_e32 v162, 1, v162
	v_lshrrev_b32_e32 v163, 1, v163
	v_lshrrev_b32_e32 v164, 1, v164
	global_load_dwordx2 v[222:223], v161, s[6:7]
	global_load_dwordx2 v[224:225], v161, s[6:7] offset:32
	global_load_dwordx2 v[226:227], v161, s[6:7] offset:256
	global_load_dwordx2 v[228:229], v161, s[6:7] offset:288
	global_load_dwordx2 v[230:231], v162, s[6:7]
	global_load_dwordx2 v[232:233], v162, s[6:7] offset:32
	global_load_dwordx2 v[234:235], v162, s[6:7] offset:256
	global_load_dwordx2 v[236:237], v162, s[6:7] offset:288
	global_load_dwordx2 v[238:239], v163, s[6:7]
	global_load_dwordx2 v[240:241], v163, s[6:7] offset:32
	global_load_dwordx2 v[242:243], v163, s[6:7] offset:256
	global_load_dwordx2 v[244:245], v163, s[6:7] offset:288
	global_load_dwordx2 v[246:247], v164, s[6:7]
	global_load_dwordx2 v[248:249], v164, s[6:7] offset:32
	global_load_dwordx2 v[250:251], v164, s[6:7] offset:256
	global_load_dwordx2 v[252:253], v164, s[6:7] offset:288

.LBB0_1418:
	v_lshl_add_u32 v144, s1, 8, v146
	v_lshl_or_b32 v142, s0, 8, v148
	v_ashrrev_i32_e32 v145, 31, v144
	v_ashrrev_i32_e32 v143, 31, v142
	v_lshl_add_u32 v220, v144, 10, v142
	v_lshlrev_b32_e32 v220, 2, v220
	v_mov_b32_e32 v204, v220
	v_lshrrev_b32_e32 v212, 1, v204
	v_add_u32_e32 v205, 0x10000, v220
	v_lshrrev_b32_e32 v213, 1, v205
	v_add_u32_e32 v206, 0x20000, v220
	v_lshrrev_b32_e32 v214, 1, v206
	v_add_u32_e32 v207, 0x30000, v220
	v_lshrrev_b32_e32 v215, 1, v207
	v_lshl_add_u32 v208, s14, 2, v220
	v_lshrrev_b32_e32 v216, 1, v208
	v_lshl_add_u32 v209, s18, 2, v220
	v_lshrrev_b32_e32 v217, 1, v209
	v_lshl_add_u32 v210, s20, 2, v220
	v_lshrrev_b32_e32 v218, 1, v210
	v_lshl_add_u32 v211, s34, 2, v220
	v_lshrrev_b32_e32 v219, 1, v211
	s_andn2_b64 vcc, exec, s[2:3]
	s_mov_b64 s[2:3], -1
	global_load_dwordx2 v[168:169], v216, s[6:7]
	global_load_dwordx2 v[170:171], v216, s[6:7] offset:32
	global_load_dwordx2 v[172:173], v216, s[6:7] offset:256
	global_load_dwordx2 v[174:175], v216, s[6:7] offset:288
	global_load_dwordx2 v[176:177], v217, s[6:7]
	global_load_dwordx2 v[178:179], v217, s[6:7] offset:32
	global_load_dwordx2 v[180:181], v217, s[6:7] offset:256
	global_load_dwordx2 v[182:183], v217, s[6:7] offset:288
	global_load_dwordx2 v[184:185], v218, s[6:7]
	global_load_dwordx2 v[186:187], v218, s[6:7] offset:32
	global_load_dwordx2 v[188:189], v218, s[6:7] offset:256
	global_load_dwordx2 v[190:191], v218, s[6:7] offset:288
	global_load_dwordx2 v[192:193], v219, s[6:7]
	global_load_dwordx2 v[194:195], v219, s[6:7] offset:32
	global_load_dwordx2 v[196:197], v219, s[6:7] offset:256
	global_load_dwordx2 v[198:199], v219, s[6:7] offset:288
	s_waitcnt vmcnt(16)
	v_lshlrev_b32_e32 v220, 16, v222
	v_and_b32_e32 v222, 0xffff0000, v222
	v_lshlrev_b32_e32 v221, 16, v223
	v_and_b32_e32 v223, 0xffff0000, v223
	v_fma_f32 v124, v220, s12, v124
	v_fma_f32 v125, v222, s12, v125
	v_fma_f32 v126, v221, s12, v126
	v_fma_f32 v127, v223, s12, v127
	global_store_dwordx4 v204, v[124:127], s[24:25]
	s_waitcnt vmcnt(17)
	v_lshlrev_b32_e32 v220, 16, v224
	v_and_b32_e32 v224, 0xffff0000, v224
	v_lshlrev_b32_e32 v221, 16, v225
	v_and_b32_e32 v225, 0xffff0000, v225
	v_fma_f32 v120, v220, s12, v120
	v_fma_f32 v121, v224, s12, v121
	v_fma_f32 v122, v221, s12, v122
	v_fma_f32 v123, v225, s12, v123
	global_store_dwordx4 v204, v[120:123], s[24:25] offset:64
	s_waitcnt vmcnt(18)
	v_lshlrev_b32_e32 v220, 16, v226
	v_and_b32_e32 v226, 0xffff0000, v226
	v_lshlrev_b32_e32 v221, 16, v227
	v_and_b32_e32 v227, 0xffff0000, v227
	v_fma_f32 v116, v220, s12, v116
	v_fma_f32 v117, v226, s12, v117
	v_fma_f32 v118, v221, s12, v118
	v_fma_f32 v119, v227, s12, v119
	global_store_dwordx4 v204, v[116:119], s[24:25] offset:512
	s_waitcnt vmcnt(19)
	v_lshlrev_b32_e32 v220, 16, v228
	v_and_b32_e32 v228, 0xffff0000, v228
	v_lshlrev_b32_e32 v221, 16, v229
	v_and_b32_e32 v229, 0xffff0000, v229
	v_fma_f32 v108, v220, s12, v108
	v_fma_f32 v109, v228, s12, v109
	v_fma_f32 v110, v221, s12, v110
	v_fma_f32 v111, v229, s12, v111
	global_store_dwordx4 v204, v[108:111], s[24:25] offset:576
	s_waitcnt vmcnt(20)
	v_lshlrev_b32_e32 v220, 16, v230
	v_and_b32_e32 v230, 0xffff0000, v230
	v_lshlrev_b32_e32 v221, 16, v231
	v_and_b32_e32 v231, 0xffff0000, v231
	v_fma_f32 v112, v220, s12, v112
	v_fma_f32 v113, v230, s12, v113
	v_fma_f32 v114, v221, s12, v114
	v_fma_f32 v115, v231, s12, v115
	global_store_dwordx4 v205, v[112:115], s[24:25]
	s_waitcnt vmcnt(21)
	v_lshlrev_b32_e32 v220, 16, v232
	v_and_b32_e32 v232, 0xffff0000, v232
	v_lshlrev_b32_e32 v221, 16, v233
	v_and_b32_e32 v233, 0xffff0000, v233
	v_fma_f32 v104, v220, s12, v104
	v_fma_f32 v105, v232, s12, v105
	v_fma_f32 v106, v221, s12, v106
	v_fma_f32 v107, v233, s12, v107
	global_store_dwordx4 v205, v[104:107], s[24:25] offset:64
	s_waitcnt vmcnt(22)
	v_lshlrev_b32_e32 v220, 16, v234
	v_and_b32_e32 v234, 0xffff0000, v234
	v_lshlrev_b32_e32 v221, 16, v235
	v_and_b32_e32 v235, 0xffff0000, v235
	v_fma_f32 v100, v220, s12, v100
	v_fma_f32 v101, v234, s12, v101
	v_fma_f32 v102, v221, s12, v102
	v_fma_f32 v103, v235, s12, v103
	global_store_dwordx4 v205, v[100:103], s[24:25] offset:512
	s_waitcnt vmcnt(23)
	v_lshlrev_b32_e32 v220, 16, v236
	v_and_b32_e32 v236, 0xffff0000, v236
	v_lshlrev_b32_e32 v221, 16, v237
	v_and_b32_e32 v237, 0xffff0000, v237
	v_fma_f32 v92, v220, s12, v92
	v_fma_f32 v93, v236, s12, v93
	v_fma_f32 v94, v221, s12, v94
	v_fma_f32 v95, v237, s12, v95
	global_store_dwordx4 v205, v[92:95], s[24:25] offset:576
	s_waitcnt vmcnt(24)
	v_lshlrev_b32_e32 v220, 16, v238
	v_and_b32_e32 v238, 0xffff0000, v238
	v_lshlrev_b32_e32 v221, 16, v239
	v_and_b32_e32 v239, 0xffff0000, v239
	v_fma_f32 v96, v220, s12, v96
	v_fma_f32 v97, v238, s12, v97
	v_fma_f32 v98, v221, s12, v98
	v_fma_f32 v99, v239, s12, v99
	global_store_dwordx4 v206, v[96:99], s[24:25]
	s_waitcnt vmcnt(25)
	v_lshlrev_b32_e32 v220, 16, v240
	v_and_b32_e32 v240, 0xffff0000, v240
	v_lshlrev_b32_e32 v221, 16, v241
	v_and_b32_e32 v241, 0xffff0000, v241
	v_fma_f32 v88, v220, s12, v88
	v_fma_f32 v89, v240, s12, v89
	v_fma_f32 v90, v221, s12, v90
	v_fma_f32 v91, v241, s12, v91
	global_store_dwordx4 v206, v[88:91], s[24:25] offset:64
	s_waitcnt vmcnt(26)
	v_lshlrev_b32_e32 v220, 16, v242
	v_and_b32_e32 v242, 0xffff0000, v242
	v_lshlrev_b32_e32 v221, 16, v243
	v_and_b32_e32 v243, 0xffff0000, v243
	v_fma_f32 v84, v220, s12, v84
	v_fma_f32 v85, v242, s12, v85
	v_fma_f32 v86, v221, s12, v86
	v_fma_f32 v87, v243, s12, v87
	global_store_dwordx4 v206, v[84:87], s[24:25] offset:512
	s_waitcnt vmcnt(27)
	v_lshlrev_b32_e32 v220, 16, v244
	v_and_b32_e32 v244, 0xffff0000, v244
	v_lshlrev_b32_e32 v221, 16, v245
	v_and_b32_e32 v245, 0xffff0000, v245
	v_fma_f32 v76, v220, s12, v76
	v_fma_f32 v77, v244, s12, v77
	v_fma_f32 v78, v221, s12, v78
	v_fma_f32 v79, v245, s12, v79
	global_store_dwordx4 v206, v[76:79], s[24:25] offset:576
	s_waitcnt vmcnt(28)
	v_lshlrev_b32_e32 v220, 16, v246
	v_and_b32_e32 v246, 0xffff0000, v246
	v_lshlrev_b32_e32 v221, 16, v247
	v_and_b32_e32 v247, 0xffff0000, v247
	v_fma_f32 v80, v220, s12, v80
	v_fma_f32 v81, v246, s12, v81
	v_fma_f32 v82, v221, s12, v82
	v_fma_f32 v83, v247, s12, v83
	global_store_dwordx4 v207, v[80:83], s[24:25]
	s_waitcnt vmcnt(29)
	v_lshlrev_b32_e32 v220, 16, v248
	v_and_b32_e32 v248, 0xffff0000, v248
	v_lshlrev_b32_e32 v221, 16, v249
	v_and_b32_e32 v249, 0xffff0000, v249
	v_fma_f32 v72, v220, s12, v72
	v_fma_f32 v73, v248, s12, v73
	v_fma_f32 v74, v221, s12, v74
	v_fma_f32 v75, v249, s12, v75
	global_store_dwordx4 v207, v[72:75], s[24:25] offset:64
	s_waitcnt vmcnt(30)
	v_lshlrev_b32_e32 v220, 16, v250
	v_and_b32_e32 v250, 0xffff0000, v250
	v_lshlrev_b32_e32 v221, 16, v251
	v_and_b32_e32 v251, 0xffff0000, v251
	v_fma_f32 v68, v220, s12, v68
	v_fma_f32 v69, v250, s12, v69
	v_fma_f32 v70, v221, s12, v70
	v_fma_f32 v71, v251, s12, v71
	global_store_dwordx4 v207, v[68:71], s[24:25] offset:512
	s_waitcnt vmcnt(31)
	v_lshlrev_b32_e32 v220, 16, v252
	v_and_b32_e32 v252, 0xffff0000, v252
	v_lshlrev_b32_e32 v221, 16, v253
	v_and_b32_e32 v253, 0xffff0000, v253
	v_fma_f32 v64, v220, s12, v64
	v_fma_f32 v65, v252, s12, v65
	v_fma_f32 v66, v221, s12, v66
	v_fma_f32 v67, v253, s12, v67
	global_store_dwordx4 v207, v[64:67], s[24:25] offset:576
	s_waitcnt vmcnt(31)
	v_lshlrev_b32_e32 v220, 16, v168
	v_and_b32_e32 v168, 0xffff0000, v168
	v_lshlrev_b32_e32 v221, 16, v169
	v_and_b32_e32 v169, 0xffff0000, v169
	v_fma_f32 v60, v220, s12, v60
	v_fma_f32 v61, v168, s12, v61
	v_fma_f32 v62, v221, s12, v62
	v_fma_f32 v63, v169, s12, v63
	global_store_dwordx4 v208, v[60:63], s[24:25]
	s_waitcnt vmcnt(31)
	v_lshlrev_b32_e32 v220, 16, v170
	v_and_b32_e32 v170, 0xffff0000, v170
	v_lshlrev_b32_e32 v221, 16, v171
	v_and_b32_e32 v171, 0xffff0000, v171
	v_fma_f32 v56, v220, s12, v56
	v_fma_f32 v57, v170, s12, v57
	v_fma_f32 v58, v221, s12, v58
	v_fma_f32 v59, v171, s12, v59
	global_store_dwordx4 v208, v[56:59], s[24:25] offset:64
	s_waitcnt vmcnt(31)
	v_lshlrev_b32_e32 v220, 16, v172
	v_and_b32_e32 v172, 0xffff0000, v172
	v_lshlrev_b32_e32 v221, 16, v173
	v_and_b32_e32 v173, 0xffff0000, v173
	v_fma_f32 v52, v220, s12, v52
	v_fma_f32 v53, v172, s12, v53
	v_fma_f32 v54, v221, s12, v54
	v_fma_f32 v55, v173, s12, v55
	global_store_dwordx4 v208, v[52:55], s[24:25] offset:512
	s_waitcnt vmcnt(31)
	v_lshlrev_b32_e32 v220, 16, v174
	v_and_b32_e32 v174, 0xffff0000, v174
	v_lshlrev_b32_e32 v221, 16, v175
	v_and_b32_e32 v175, 0xffff0000, v175
	v_fma_f32 v44, v220, s12, v44
	v_fma_f32 v45, v174, s12, v45
	v_fma_f32 v46, v221, s12, v46
	v_fma_f32 v47, v175, s12, v47
	global_store_dwordx4 v208, v[44:47], s[24:25] offset:576
	s_waitcnt vmcnt(31)
	v_lshlrev_b32_e32 v220, 16, v176
	v_and_b32_e32 v176, 0xffff0000, v176
	v_lshlrev_b32_e32 v221, 16, v177
	v_and_b32_e32 v177, 0xffff0000, v177
	v_fma_f32 v48, v220, s12, v48
	v_fma_f32 v49, v176, s12, v49
	v_fma_f32 v50, v221, s12, v50
	v_fma_f32 v51, v177, s12, v51
	global_store_dwordx4 v209, v[48:51], s[24:25]
	s_waitcnt vmcnt(31)
	v_lshlrev_b32_e32 v220, 16, v178
	v_and_b32_e32 v178, 0xffff0000, v178
	v_lshlrev_b32_e32 v221, 16, v179
	v_and_b32_e32 v179, 0xffff0000, v179
	v_fma_f32 v40, v220, s12, v40
	v_fma_f32 v41, v178, s12, v41
	v_fma_f32 v42, v221, s12, v42
	v_fma_f32 v43, v179, s12, v43
	global_store_dwordx4 v209, v[40:43], s[24:25] offset:64
	s_waitcnt vmcnt(31)
	v_lshlrev_b32_e32 v220, 16, v180
	v_and_b32_e32 v180, 0xffff0000, v180
	v_lshlrev_b32_e32 v221, 16, v181
	v_and_b32_e32 v181, 0xffff0000, v181
	v_fma_f32 v36, v220, s12, v36
	v_fma_f32 v37, v180, s12, v37
	v_fma_f32 v38, v221, s12, v38
	v_fma_f32 v39, v181, s12, v39
	global_store_dwordx4 v209, v[36:39], s[24:25] offset:512
	s_waitcnt vmcnt(31)
	v_lshlrev_b32_e32 v220, 16, v182
	v_and_b32_e32 v182, 0xffff0000, v182
	v_lshlrev_b32_e32 v221, 16, v183
	v_and_b32_e32 v183, 0xffff0000, v183
	v_fma_f32 v28, v220, s12, v28
	v_fma_f32 v29, v182, s12, v29
	v_fma_f32 v30, v221, s12, v30
	v_fma_f32 v31, v183, s12, v31
	global_store_dwordx4 v209, v[28:31], s[24:25] offset:576
	s_waitcnt vmcnt(31)
	v_lshlrev_b32_e32 v220, 16, v184
	v_and_b32_e32 v184, 0xffff0000, v184
	v_lshlrev_b32_e32 v221, 16, v185
	v_and_b32_e32 v185, 0xffff0000, v185
	v_fma_f32 v32, v220, s12, v32
	v_fma_f32 v33, v184, s12, v33
	v_fma_f32 v34, v221, s12, v34
	v_fma_f32 v35, v185, s12, v35
	global_store_dwordx4 v210, v[32:35], s[24:25]
	s_waitcnt vmcnt(31)
	v_lshlrev_b32_e32 v220, 16, v186
	v_and_b32_e32 v186, 0xffff0000, v186
	v_lshlrev_b32_e32 v221, 16, v187
	v_and_b32_e32 v187, 0xffff0000, v187
	v_fma_f32 v24, v220, s12, v24
	v_fma_f32 v25, v186, s12, v25
	v_fma_f32 v26, v221, s12, v26
	v_fma_f32 v27, v187, s12, v27
	global_store_dwordx4 v210, v[24:27], s[24:25] offset:64
	s_waitcnt vmcnt(31)
	v_lshlrev_b32_e32 v220, 16, v188
	v_and_b32_e32 v188, 0xffff0000, v188
	v_lshlrev_b32_e32 v221, 16, v189
	v_and_b32_e32 v189, 0xffff0000, v189
	v_fma_f32 v20, v220, s12, v20
	v_fma_f32 v21, v188, s12, v21
	v_fma_f32 v22, v221, s12, v22
	v_fma_f32 v23, v189, s12, v23
	global_store_dwordx4 v210, v[20:23], s[24:25] offset:512
	s_waitcnt vmcnt(31)
	v_lshlrev_b32_e32 v220, 16, v190
	v_and_b32_e32 v190, 0xffff0000, v190
	v_lshlrev_b32_e32 v221, 16, v191
	v_and_b32_e32 v191, 0xffff0000, v191
	v_fma_f32 v12, v220, s12, v12
	v_fma_f32 v13, v190, s12, v13
	v_fma_f32 v14, v221, s12, v14
	v_fma_f32 v15, v191, s12, v15
	global_store_dwordx4 v210, v[12:15], s[24:25] offset:576
	s_waitcnt vmcnt(31)
	v_lshlrev_b32_e32 v220, 16, v192
	v_and_b32_e32 v192, 0xffff0000, v192
	v_lshlrev_b32_e32 v221, 16, v193
	v_and_b32_e32 v193, 0xffff0000, v193
	v_fma_f32 v16, v220, s12, v16
	v_fma_f32 v17, v192, s12, v17
	v_fma_f32 v18, v221, s12, v18
	v_fma_f32 v19, v193, s12, v19
	global_store_dwordx4 v211, v[16:19], s[24:25]
	s_waitcnt vmcnt(31)
	v_lshlrev_b32_e32 v220, 16, v194
	v_and_b32_e32 v194, 0xffff0000, v194
	v_lshlrev_b32_e32 v221, 16, v195
	v_and_b32_e32 v195, 0xffff0000, v195
	v_fma_f32 v8, v220, s12, v8
	v_fma_f32 v9, v194, s12, v9
	v_fma_f32 v10, v221, s12, v10
	v_fma_f32 v11, v195, s12, v11
	global_store_dwordx4 v211, v[8:11], s[24:25] offset:64
	s_waitcnt vmcnt(31)
	v_lshlrev_b32_e32 v220, 16, v196
	v_and_b32_e32 v196, 0xffff0000, v196
	v_lshlrev_b32_e32 v221, 16, v197
	v_and_b32_e32 v197, 0xffff0000, v197
	v_fma_f32 v4, v220, s12, v4
	v_fma_f32 v5, v196, s12, v5
	v_fma_f32 v6, v221, s12, v6
	v_fma_f32 v7, v197, s12, v7
	global_store_dwordx4 v211, v[4:7], s[24:25] offset:512
	s_waitcnt vmcnt(31)
	v_lshlrev_b32_e32 v220, 16, v198
	v_and_b32_e32 v198, 0xffff0000, v198
	v_lshlrev_b32_e32 v221, 16, v199
	v_and_b32_e32 v199, 0xffff0000, v199
	v_fma_f32 v0, v220, s12, v0
	v_fma_f32 v1, v198, s12, v1
	v_fma_f32 v2, v221, s12, v2
	v_fma_f32 v3, v199, s12, v3
	global_store_dwordx4 v211, v[0:3], s[24:25] offset:576
	s_cbranch_vccnz .LBB0_1411
	s_andn2_b64 vcc, exec, s[4:5]
	s_cbranch_vccnz .LBB0_1410
	s_barrier
	s_branch .LBB0_1410

.LBB0_1703:
	s_add_u32 s44, s44, 0xb0080
	s_addc_u32 s45, s45, 0
	s_add_u32 s66, s46, 0x100
	s_addc_u32 s67, s47, 0
	s_mov_b32 s68, -2
	v_mov_b64_e32 v[0:1], 0
	v_mov_b64_e32 v[2:3], 0
	v_mov_b64_e32 v[4:5], 0
	v_mov_b64_e32 v[6:7], 0
	v_mov_b64_e32 v[8:9], 0
	v_mov_b64_e32 v[10:11], 0
	v_mov_b64_e32 v[12:13], 0
	v_mov_b64_e32 v[14:15], 0
	v_mov_b64_e32 v[16:17], 0
	v_mov_b64_e32 v[18:19], 0
	v_mov_b64_e32 v[20:21], 0
	v_mov_b64_e32 v[22:23], 0
	v_mov_b64_e32 v[24:25], 0
	v_mov_b64_e32 v[26:27], 0
	v_mov_b64_e32 v[28:29], 0
	v_mov_b64_e32 v[30:31], 0
	v_mov_b64_e32 v[32:33], 0
	v_mov_b64_e32 v[34:35], 0
	v_mov_b64_e32 v[36:37], 0
	v_mov_b64_e32 v[38:39], 0
	v_mov_b64_e32 v[40:41], 0
	v_mov_b64_e32 v[42:43], 0
	v_mov_b64_e32 v[44:45], 0
	v_mov_b64_e32 v[46:47], 0
	v_mov_b64_e32 v[48:49], 0
	v_mov_b64_e32 v[50:51], 0
	v_mov_b64_e32 v[52:53], 0
	v_mov_b64_e32 v[54:55], 0
	v_mov_b64_e32 v[56:57], 0
	v_mov_b64_e32 v[58:59], 0
	v_mov_b64_e32 v[60:61], 0
	v_mov_b64_e32 v[62:63], 0
	v_mov_b64_e32 v[64:65], 0
	v_mov_b64_e32 v[66:67], 0
	v_mov_b64_e32 v[68:69], 0
	v_mov_b64_e32 v[70:71], 0
	v_mov_b64_e32 v[72:73], 0
	v_mov_b64_e32 v[74:75], 0
	v_mov_b64_e32 v[76:77], 0
	v_mov_b64_e32 v[78:79], 0
	v_mov_b64_e32 v[80:81], 0
	v_mov_b64_e32 v[82:83], 0
	v_mov_b64_e32 v[84:85], 0
	v_mov_b64_e32 v[86:87], 0
	v_mov_b64_e32 v[88:89], 0
	v_mov_b64_e32 v[90:91], 0
	v_mov_b64_e32 v[92:93], 0
	v_mov_b64_e32 v[94:95], 0
	v_mov_b64_e32 v[96:97], 0
	v_mov_b64_e32 v[98:99], 0
	v_mov_b64_e32 v[100:101], 0
	v_mov_b64_e32 v[102:103], 0
	v_mov_b64_e32 v[104:105], 0
	v_mov_b64_e32 v[106:107], 0
	v_mov_b64_e32 v[108:109], 0
	v_mov_b64_e32 v[110:111], 0
	v_mov_b64_e32 v[112:113], 0
	v_mov_b64_e32 v[114:115], 0
	v_mov_b64_e32 v[116:117], 0
	v_mov_b64_e32 v[118:119], 0
	v_mov_b64_e32 v[120:121], 0
	v_mov_b64_e32 v[122:123], 0
	v_mov_b64_e32 v[124:125], 0
	v_mov_b64_e32 v[126:127], 0
	s_waitcnt vmcnt(0)
	v_lshl_add_u32 v160, s1, 8, v146
	v_lshl_or_b32 v161, s0, 8, v148
	v_lshl_add_u32 v160, v160, 10, v161
	v_lshlrev_b32_e32 v160, 2, v160
	v_mov_b32_e32 v161, v160
	v_add_u32_e32 v162, 0x10000, v160
	v_add_u32_e32 v163, 0x20000, v160
	v_add_u32_e32 v164, 0x30000, v160
	v_lshrrev_b32_e32 v161, 1, v161
	v_lshrrev_b32_e32 v162, 1, v162
	v_lshrrev_b32_e32 v163, 1, v163
	v_lshrrev_b32_e32 v164, 1, v164
	global_load_dwordx2 v[222:223], v161, s[8:9]
	global_load_dwordx2 v[224:225], v161, s[8:9] offset:32
	global_load_dwordx2 v[226:227], v161, s[8:9] offset:256
	global_load_dwordx2 v[228:229], v161, s[8:9] offset:288
	global_load_dwordx2 v[230:231], v162, s[8:9]
	global_load_dwordx2 v[232:233], v162, s[8:9] offset:32
	global_load_dwordx2 v[234:235], v162, s[8:9] offset:256
	global_load_dwordx2 v[236:237], v162, s[8:9] offset:288
	global_load_dwordx2 v[238:239], v163, s[8:9]
	global_load_dwordx2 v[240:241], v163, s[8:9] offset:32
	global_load_dwordx2 v[242:243], v163, s[8:9] offset:256
	global_load_dwordx2 v[244:245], v163, s[8:9] offset:288
	global_load_dwordx2 v[246:247], v164, s[8:9]
	global_load_dwordx2 v[248:249], v164, s[8:9] offset:32
	global_load_dwordx2 v[250:251], v164, s[8:9] offset:256
	global_load_dwordx2 v[252:253], v164, s[8:9] offset:288

.LBB0_1707:
	v_lshl_add_u32 v144, s1, 8, v146
	v_lshl_or_b32 v142, s0, 8, v148
	v_ashrrev_i32_e32 v145, 31, v144
	v_ashrrev_i32_e32 v143, 31, v142
	v_lshl_add_u32 v220, v144, 10, v142
	v_lshlrev_b32_e32 v220, 2, v220
	v_mov_b32_e32 v204, v220
	v_lshrrev_b32_e32 v212, 1, v204
	v_add_u32_e32 v205, 0x10000, v220
	v_lshrrev_b32_e32 v213, 1, v205
	v_add_u32_e32 v206, 0x20000, v220
	v_lshrrev_b32_e32 v214, 1, v206
	v_add_u32_e32 v207, 0x30000, v220
	v_lshrrev_b32_e32 v215, 1, v207
	v_lshl_add_u32 v208, s18, 2, v220
	v_lshrrev_b32_e32 v216, 1, v208
	v_lshl_add_u32 v209, s20, 2, v220
	v_lshrrev_b32_e32 v217, 1, v209
	v_lshl_add_u32 v210, s34, 2, v220
	v_lshrrev_b32_e32 v218, 1, v210
	v_lshl_add_u32 v211, s36, 2, v220
	v_lshrrev_b32_e32 v219, 1, v211
	s_and_b64 vcc, exec, s[2:3]
	s_mov_b64 s[2:3], -1
	global_load_dwordx2 v[168:169], v216, s[8:9]
	global_load_dwordx2 v[170:171], v216, s[8:9] offset:32
	global_load_dwordx2 v[172:173], v216, s[8:9] offset:256
	global_load_dwordx2 v[174:175], v216, s[8:9] offset:288
	global_load_dwordx2 v[176:177], v217, s[8:9]
	global_load_dwordx2 v[178:179], v217, s[8:9] offset:32
	global_load_dwordx2 v[180:181], v217, s[8:9] offset:256
	global_load_dwordx2 v[182:183], v217, s[8:9] offset:288
	global_load_dwordx2 v[184:185], v218, s[8:9]
	global_load_dwordx2 v[186:187], v218, s[8:9] offset:32
	global_load_dwordx2 v[188:189], v218, s[8:9] offset:256
	global_load_dwordx2 v[190:191], v218, s[8:9] offset:288
	global_load_dwordx2 v[192:193], v219, s[8:9]
	global_load_dwordx2 v[194:195], v219, s[8:9] offset:32
	global_load_dwordx2 v[196:197], v219, s[8:9] offset:256
	global_load_dwordx2 v[198:199], v219, s[8:9] offset:288
	s_waitcnt vmcnt(16)
	v_lshlrev_b32_e32 v220, 16, v222
	v_and_b32_e32 v222, 0xffff0000, v222
	v_lshlrev_b32_e32 v221, 16, v223
	v_and_b32_e32 v223, 0xffff0000, v223
	v_fma_f32 v124, v220, s14, v124
	v_fma_f32 v125, v222, s14, v125
	v_fma_f32 v126, v221, s14, v126
	v_fma_f32 v127, v223, s14, v127
	global_store_dwordx4 v204, v[124:127], s[24:25]
	s_waitcnt vmcnt(17)
	v_lshlrev_b32_e32 v220, 16, v224
	v_and_b32_e32 v224, 0xffff0000, v224
	v_lshlrev_b32_e32 v221, 16, v225
	v_and_b32_e32 v225, 0xffff0000, v225
	v_fma_f32 v120, v220, s14, v120
	v_fma_f32 v121, v224, s14, v121
	v_fma_f32 v122, v221, s14, v122
	v_fma_f32 v123, v225, s14, v123
	global_store_dwordx4 v204, v[120:123], s[24:25] offset:64
	s_waitcnt vmcnt(18)
	v_lshlrev_b32_e32 v220, 16, v226
	v_and_b32_e32 v226, 0xffff0000, v226
	v_lshlrev_b32_e32 v221, 16, v227
	v_and_b32_e32 v227, 0xffff0000, v227
	v_fma_f32 v116, v220, s14, v116
	v_fma_f32 v117, v226, s14, v117
	v_fma_f32 v118, v221, s14, v118
	v_fma_f32 v119, v227, s14, v119
	global_store_dwordx4 v204, v[116:119], s[24:25] offset:512
	s_waitcnt vmcnt(19)
	v_lshlrev_b32_e32 v220, 16, v228
	v_and_b32_e32 v228, 0xffff0000, v228
	v_lshlrev_b32_e32 v221, 16, v229
	v_and_b32_e32 v229, 0xffff0000, v229
	v_fma_f32 v108, v220, s14, v108
	v_fma_f32 v109, v228, s14, v109
	v_fma_f32 v110, v221, s14, v110
	v_fma_f32 v111, v229, s14, v111
	global_store_dwordx4 v204, v[108:111], s[24:25] offset:576
	s_waitcnt vmcnt(20)
	v_lshlrev_b32_e32 v220, 16, v230
	v_and_b32_e32 v230, 0xffff0000, v230
	v_lshlrev_b32_e32 v221, 16, v231
	v_and_b32_e32 v231, 0xffff0000, v231
	v_fma_f32 v112, v220, s14, v112
	v_fma_f32 v113, v230, s14, v113
	v_fma_f32 v114, v221, s14, v114
	v_fma_f32 v115, v231, s14, v115
	global_store_dwordx4 v205, v[112:115], s[24:25]
	s_waitcnt vmcnt(21)
	v_lshlrev_b32_e32 v220, 16, v232
	v_and_b32_e32 v232, 0xffff0000, v232
	v_lshlrev_b32_e32 v221, 16, v233
	v_and_b32_e32 v233, 0xffff0000, v233
	v_fma_f32 v104, v220, s14, v104
	v_fma_f32 v105, v232, s14, v105
	v_fma_f32 v106, v221, s14, v106
	v_fma_f32 v107, v233, s14, v107
	global_store_dwordx4 v205, v[104:107], s[24:25] offset:64
	s_waitcnt vmcnt(22)
	v_lshlrev_b32_e32 v220, 16, v234
	v_and_b32_e32 v234, 0xffff0000, v234
	v_lshlrev_b32_e32 v221, 16, v235
	v_and_b32_e32 v235, 0xffff0000, v235
	v_fma_f32 v100, v220, s14, v100
	v_fma_f32 v101, v234, s14, v101
	v_fma_f32 v102, v221, s14, v102
	v_fma_f32 v103, v235, s14, v103
	global_store_dwordx4 v205, v[100:103], s[24:25] offset:512
	s_waitcnt vmcnt(23)
	v_lshlrev_b32_e32 v220, 16, v236
	v_and_b32_e32 v236, 0xffff0000, v236
	v_lshlrev_b32_e32 v221, 16, v237
	v_and_b32_e32 v237, 0xffff0000, v237
	v_fma_f32 v92, v220, s14, v92
	v_fma_f32 v93, v236, s14, v93
	v_fma_f32 v94, v221, s14, v94
	v_fma_f32 v95, v237, s14, v95
	global_store_dwordx4 v205, v[92:95], s[24:25] offset:576
	s_waitcnt vmcnt(24)
	v_lshlrev_b32_e32 v220, 16, v238
	v_and_b32_e32 v238, 0xffff0000, v238
	v_lshlrev_b32_e32 v221, 16, v239
	v_and_b32_e32 v239, 0xffff0000, v239
	v_fma_f32 v96, v220, s14, v96
	v_fma_f32 v97, v238, s14, v97
	v_fma_f32 v98, v221, s14, v98
	v_fma_f32 v99, v239, s14, v99
	global_store_dwordx4 v206, v[96:99], s[24:25]
	s_waitcnt vmcnt(25)
	v_lshlrev_b32_e32 v220, 16, v240
	v_and_b32_e32 v240, 0xffff0000, v240
	v_lshlrev_b32_e32 v221, 16, v241
	v_and_b32_e32 v241, 0xffff0000, v241
	v_fma_f32 v88, v220, s14, v88
	v_fma_f32 v89, v240, s14, v89
	v_fma_f32 v90, v221, s14, v90
	v_fma_f32 v91, v241, s14, v91
	global_store_dwordx4 v206, v[88:91], s[24:25] offset:64
	s_waitcnt vmcnt(26)
	v_lshlrev_b32_e32 v220, 16, v242
	v_and_b32_e32 v242, 0xffff0000, v242
	v_lshlrev_b32_e32 v221, 16, v243
	v_and_b32_e32 v243, 0xffff0000, v243
	v_fma_f32 v84, v220, s14, v84
	v_fma_f32 v85, v242, s14, v85
	v_fma_f32 v86, v221, s14, v86
	v_fma_f32 v87, v243, s14, v87
	global_store_dwordx4 v206, v[84:87], s[24:25] offset:512
	s_waitcnt vmcnt(27)
	v_lshlrev_b32_e32 v220, 16, v244
	v_and_b32_e32 v244, 0xffff0000, v244
	v_lshlrev_b32_e32 v221, 16, v245
	v_and_b32_e32 v245, 0xffff0000, v245
	v_fma_f32 v76, v220, s14, v76
	v_fma_f32 v77, v244, s14, v77
	v_fma_f32 v78, v221, s14, v78
	v_fma_f32 v79, v245, s14, v79
	global_store_dwordx4 v206, v[76:79], s[24:25] offset:576
	s_waitcnt vmcnt(28)
	v_lshlrev_b32_e32 v220, 16, v246
	v_and_b32_e32 v246, 0xffff0000, v246
	v_lshlrev_b32_e32 v221, 16, v247
	v_and_b32_e32 v247, 0xffff0000, v247
	v_fma_f32 v80, v220, s14, v80
	v_fma_f32 v81, v246, s14, v81
	v_fma_f32 v82, v221, s14, v82
	v_fma_f32 v83, v247, s14, v83
	global_store_dwordx4 v207, v[80:83], s[24:25]
	s_waitcnt vmcnt(29)
	v_lshlrev_b32_e32 v220, 16, v248
	v_and_b32_e32 v248, 0xffff0000, v248
	v_lshlrev_b32_e32 v221, 16, v249
	v_and_b32_e32 v249, 0xffff0000, v249
	v_fma_f32 v72, v220, s14, v72
	v_fma_f32 v73, v248, s14, v73
	v_fma_f32 v74, v221, s14, v74
	v_fma_f32 v75, v249, s14, v75
	global_store_dwordx4 v207, v[72:75], s[24:25] offset:64
	s_waitcnt vmcnt(30)
	v_lshlrev_b32_e32 v220, 16, v250
	v_and_b32_e32 v250, 0xffff0000, v250
	v_lshlrev_b32_e32 v221, 16, v251
	v_and_b32_e32 v251, 0xffff0000, v251
	v_fma_f32 v68, v220, s14, v68
	v_fma_f32 v69, v250, s14, v69
	v_fma_f32 v70, v221, s14, v70
	v_fma_f32 v71, v251, s14, v71
	global_store_dwordx4 v207, v[68:71], s[24:25] offset:512
	s_waitcnt vmcnt(31)
	v_lshlrev_b32_e32 v220, 16, v252
	v_and_b32_e32 v252, 0xffff0000, v252
	v_lshlrev_b32_e32 v221, 16, v253
	v_and_b32_e32 v253, 0xffff0000, v253
	v_fma_f32 v64, v220, s14, v64
	v_fma_f32 v65, v252, s14, v65
	v_fma_f32 v66, v221, s14, v66
	v_fma_f32 v67, v253, s14, v67
	global_store_dwordx4 v207, v[64:67], s[24:25] offset:576
	s_waitcnt vmcnt(31)
	v_lshlrev_b32_e32 v220, 16, v168
	v_and_b32_e32 v168, 0xffff0000, v168
	v_lshlrev_b32_e32 v221, 16, v169
	v_and_b32_e32 v169, 0xffff0000, v169
	v_fma_f32 v60, v220, s14, v60
	v_fma_f32 v61, v168, s14, v61
	v_fma_f32 v62, v221, s14, v62
	v_fma_f32 v63, v169, s14, v63
	global_store_dwordx4 v208, v[60:63], s[24:25]
	s_waitcnt vmcnt(31)
	v_lshlrev_b32_e32 v220, 16, v170
	v_and_b32_e32 v170, 0xffff0000, v170
	v_lshlrev_b32_e32 v221, 16, v171
	v_and_b32_e32 v171, 0xffff0000, v171
	v_fma_f32 v56, v220, s14, v56
	v_fma_f32 v57, v170, s14, v57
	v_fma_f32 v58, v221, s14, v58
	v_fma_f32 v59, v171, s14, v59
	global_store_dwordx4 v208, v[56:59], s[24:25] offset:64
	s_waitcnt vmcnt(31)
	v_lshlrev_b32_e32 v220, 16, v172
	v_and_b32_e32 v172, 0xffff0000, v172
	v_lshlrev_b32_e32 v221, 16, v173
	v_and_b32_e32 v173, 0xffff0000, v173
	v_fma_f32 v52, v220, s14, v52
	v_fma_f32 v53, v172, s14, v53
	v_fma_f32 v54, v221, s14, v54
	v_fma_f32 v55, v173, s14, v55
	global_store_dwordx4 v208, v[52:55], s[24:25] offset:512
	s_waitcnt vmcnt(31)
	v_lshlrev_b32_e32 v220, 16, v174
	v_and_b32_e32 v174, 0xffff0000, v174
	v_lshlrev_b32_e32 v221, 16, v175
	v_and_b32_e32 v175, 0xffff0000, v175
	v_fma_f32 v44, v220, s14, v44
	v_fma_f32 v45, v174, s14, v45
	v_fma_f32 v46, v221, s14, v46
	v_fma_f32 v47, v175, s14, v47
	global_store_dwordx4 v208, v[44:47], s[24:25] offset:576
	s_waitcnt vmcnt(31)
	v_lshlrev_b32_e32 v220, 16, v176
	v_and_b32_e32 v176, 0xffff0000, v176
	v_lshlrev_b32_e32 v221, 16, v177
	v_and_b32_e32 v177, 0xffff0000, v177
	v_fma_f32 v48, v220, s14, v48
	v_fma_f32 v49, v176, s14, v49
	v_fma_f32 v50, v221, s14, v50
	v_fma_f32 v51, v177, s14, v51
	global_store_dwordx4 v209, v[48:51], s[24:25]
	s_waitcnt vmcnt(31)
	v_lshlrev_b32_e32 v220, 16, v178
	v_and_b32_e32 v178, 0xffff0000, v178
	v_lshlrev_b32_e32 v221, 16, v179
	v_and_b32_e32 v179, 0xffff0000, v179
	v_fma_f32 v40, v220, s14, v40
	v_fma_f32 v41, v178, s14, v41
	v_fma_f32 v42, v221, s14, v42
	v_fma_f32 v43, v179, s14, v43
	global_store_dwordx4 v209, v[40:43], s[24:25] offset:64
	s_waitcnt vmcnt(31)
	v_lshlrev_b32_e32 v220, 16, v180
	v_and_b32_e32 v180, 0xffff0000, v180
	v_lshlrev_b32_e32 v221, 16, v181
	v_and_b32_e32 v181, 0xffff0000, v181
	v_fma_f32 v36, v220, s14, v36
	v_fma_f32 v37, v180, s14, v37
	v_fma_f32 v38, v221, s14, v38
	v_fma_f32 v39, v181, s14, v39
	global_store_dwordx4 v209, v[36:39], s[24:25] offset:512
	s_waitcnt vmcnt(31)
	v_lshlrev_b32_e32 v220, 16, v182
	v_and_b32_e32 v182, 0xffff0000, v182
	v_lshlrev_b32_e32 v221, 16, v183
	v_and_b32_e32 v183, 0xffff0000, v183
	v_fma_f32 v28, v220, s14, v28
	v_fma_f32 v29, v182, s14, v29
	v_fma_f32 v30, v221, s14, v30
	v_fma_f32 v31, v183, s14, v31
	global_store_dwordx4 v209, v[28:31], s[24:25] offset:576
	s_waitcnt vmcnt(31)
	v_lshlrev_b32_e32 v220, 16, v184
	v_and_b32_e32 v184, 0xffff0000, v184
	v_lshlrev_b32_e32 v221, 16, v185
	v_and_b32_e32 v185, 0xffff0000, v185
	v_fma_f32 v32, v220, s14, v32
	v_fma_f32 v33, v184, s14, v33
	v_fma_f32 v34, v221, s14, v34
	v_fma_f32 v35, v185, s14, v35
	global_store_dwordx4 v210, v[32:35], s[24:25]
	s_waitcnt vmcnt(31)
	v_lshlrev_b32_e32 v220, 16, v186
	v_and_b32_e32 v186, 0xffff0000, v186
	v_lshlrev_b32_e32 v221, 16, v187
	v_and_b32_e32 v187, 0xffff0000, v187
	v_fma_f32 v24, v220, s14, v24
	v_fma_f32 v25, v186, s14, v25
	v_fma_f32 v26, v221, s14, v26
	v_fma_f32 v27, v187, s14, v27
	global_store_dwordx4 v210, v[24:27], s[24:25] offset:64
	s_waitcnt vmcnt(31)
	v_lshlrev_b32_e32 v220, 16, v188
	v_and_b32_e32 v188, 0xffff0000, v188
	v_lshlrev_b32_e32 v221, 16, v189
	v_and_b32_e32 v189, 0xffff0000, v189
	v_fma_f32 v20, v220, s14, v20
	v_fma_f32 v21, v188, s14, v21
	v_fma_f32 v22, v221, s14, v22
	v_fma_f32 v23, v189, s14, v23
	global_store_dwordx4 v210, v[20:23], s[24:25] offset:512
	s_waitcnt vmcnt(31)
	v_lshlrev_b32_e32 v220, 16, v190
	v_and_b32_e32 v190, 0xffff0000, v190
	v_lshlrev_b32_e32 v221, 16, v191
	v_and_b32_e32 v191, 0xffff0000, v191
	v_fma_f32 v12, v220, s14, v12
	v_fma_f32 v13, v190, s14, v13
	v_fma_f32 v14, v221, s14, v14
	v_fma_f32 v15, v191, s14, v15
	global_store_dwordx4 v210, v[12:15], s[24:25] offset:576
	s_waitcnt vmcnt(31)
	v_lshlrev_b32_e32 v220, 16, v192
	v_and_b32_e32 v192, 0xffff0000, v192
	v_lshlrev_b32_e32 v221, 16, v193
	v_and_b32_e32 v193, 0xffff0000, v193
	v_fma_f32 v16, v220, s14, v16
	v_fma_f32 v17, v192, s14, v17
	v_fma_f32 v18, v221, s14, v18
	v_fma_f32 v19, v193, s14, v19
	global_store_dwordx4 v211, v[16:19], s[24:25]
	s_waitcnt vmcnt(31)
	v_lshlrev_b32_e32 v220, 16, v194
	v_and_b32_e32 v194, 0xffff0000, v194
	v_lshlrev_b32_e32 v221, 16, v195
	v_and_b32_e32 v195, 0xffff0000, v195
	v_fma_f32 v8, v220, s14, v8
	v_fma_f32 v9, v194, s14, v9
	v_fma_f32 v10, v221, s14, v10
	v_fma_f32 v11, v195, s14, v11
	global_store_dwordx4 v211, v[8:11], s[24:25] offset:64
	s_waitcnt vmcnt(31)
	v_lshlrev_b32_e32 v220, 16, v196
	v_and_b32_e32 v196, 0xffff0000, v196
	v_lshlrev_b32_e32 v221, 16, v197
	v_and_b32_e32 v197, 0xffff0000, v197
	v_fma_f32 v4, v220, s14, v4
	v_fma_f32 v5, v196, s14, v5
	v_fma_f32 v6, v221, s14, v6
	v_fma_f32 v7, v197, s14, v7
	global_store_dwordx4 v211, v[4:7], s[24:25] offset:512
	s_waitcnt vmcnt(31)
	v_lshlrev_b32_e32 v220, 16, v198
	v_and_b32_e32 v198, 0xffff0000, v198
	v_lshlrev_b32_e32 v221, 16, v199
	v_and_b32_e32 v199, 0xffff0000, v199
	v_fma_f32 v0, v220, s14, v0
	v_fma_f32 v1, v198, s14, v1
	v_fma_f32 v2, v221, s14, v2
	v_fma_f32 v3, v199, s14, v3
	global_store_dwordx4 v211, v[0:3], s[24:25] offset:576
	s_cbranch_vccnz .LBB0_1696
	s_andn2_b64 vcc, exec, s[6:7]
	s_cbranch_vccnz .LBB0_1695
	s_barrier
	s_branch .LBB0_1695
